# dead padding (124 bytes) after the attention tile-list code so the later phases keep their earlier code alignment
# baseline (speedup 1.0000x reference)
; DI void attn_unit(LAS unsigned char* lds, const Args& a, int bg, int qt) {
;     ...
;         if (w == 0) {
;             int ln = lane; asm volatile("" : "+v"(ln));
;             unsigned U = MSK[ln];
; #pragma unroll
;             for (int of = 1; of < 64; of <<= 1) U |= (unsigned)__shfl_xor((int)U, of);
;             const int n = __popc(U), j0 = qt - 8 < 0 ? 0 : qt - 8;
;             if (ln < 32) { if ((U >> ln) & 1u) LIST[__popc(U & ((1u << ln) - 1u))] = ln; }
;             else if (j0 + (ln - 32) <= qt) LIST[n + ln - 32] = j0 + (ln - 32);
;             if (ln == 0) { LIST[64] = n; LIST[65] = n + (qt - j0 + 1); }
.LBB0_881:
	v_lshrrev_b32_e32 v39, v35, v38
	v_and_b32_e32 v39, 1, v39
	v_cmp_eq_u32_e32 vcc, 1, v39
	s_and_saveexec_b64 s[12:13], vcc
	v_bfe_u32 v38, v38, 0, v35
	v_bcnt_u32_b32 v38, v38, 0
	v_lshl_add_u32 v38, v38, 2, 0
	v_add_u32_e32 v38, 0x1a800, v38
	ds_write_b32 v38, v35
	s_or_b64 exec, exec, s[12:13]
	s_or_b64 exec, exec, s[10:11]
	v_cmp_eq_u32_e32 vcc, 0, v35
	s_and_saveexec_b64 s[10:11], vcc
	s_cbranch_execnz .LBB0_869
	s_branch .LBB0_870
	s_nop 0
	s_nop 0
	s_nop 0
	s_nop 0
	s_nop 0
	s_nop 0
	s_nop 0
	s_nop 0
	s_nop 0
	s_nop 0
	s_nop 0
	s_nop 0
	s_nop 0
	s_nop 0
	s_nop 0
	s_nop 0
	s_nop 0
	s_nop 0
	s_nop 0
	s_nop 0
	s_nop 0
	s_nop 0
	s_nop 0
	s_nop 0
	s_nop 0
	s_nop 0
	s_nop 0
	s_nop 0
	s_nop 0
	s_nop 0
	s_nop 0
